# v016 plus: P5 per-token loop loads merged into one round trip; gain-load hoist also in the sample-row norm loops (with store-data hazard pad)
# speedup vs baseline: 1.0134x; 1.0011x over previous
; __device__ __forceinline__ unsigned cvtpk(float lo, float hi) { unsigned r; asm volatile("v_cvt_pk_bf16_f32 %0, %1, %2" : "=v"(r) : "v"(lo), "v"(hi)); return r; }
; __device__ __forceinline__ void norm_rows_mixed(const bf16_t* xb, const float* xs, const float* g, bf16_t* xn) {
;     ...
;     for (int row = MP + gw; row < MT; row += nw) {
;         const float* xr = xs + (size_t)(row - MP) * DM; f32x4 v[8]; float ss = 0.f;
; #pragma unroll
;         for (int i = 0; i < 8; ++i) { v[i] = *(const f32x4*)(xr + (i * 64 + lane) * 4); ss += v[i][0] * v[i][0] + v[i][1] * v[i][1] + v[i][2] * v[i][2] + v[i][3] * v[i][3]; }
;         ss = wave_sum(ss); const float rs = rsqrtf(ss * (1.0f / DM) + EPS);
; #pragma unroll
;         for (int i = 0; i < 8; ++i) { const f32x4 gg = *(const f32x4*)(g + (i * 64 + lane) * 4);
;             u32x2 o; o.x = cvtpk(v[i][0] * rs * gg[0], v[i][1] * rs * gg[1]); o.y = cvtpk(v[i][2] * rs * gg[2], v[i][3] * rs * gg[3]);
;             *(u32x2*)(xn + (size_t)row * DM + (i * 64 + lane) * 4) = o; }
;     }
.LBB0_310:
	s_or_b64 exec, exec, s[6:7]
	s_movk_i32 s2, 0x200
	v_cmp_gt_i32_e32 vcc, s2, v2
	s_and_saveexec_b64 s[6:7], vcc
	s_cbranch_execz .LBB0_313
	v_mbcnt_lo_u32_b32 v4, -1, 0
	v_mbcnt_hi_u32_b32 v4, -1, v4
	v_and_b32_e32 v5, 64, v4
	v_add_u32_e32 v5, 64, v5
	v_xor_b32_e32 v17, 32, v4
	v_cmp_lt_i32_e32 vcc, v17, v5
	v_add_u32_e32 v16, 0x8000, v2
	v_lshlrev_b64 v[2:3], 13, v[2:3]
	v_cndmask_b32_e32 v17, v4, v17, vcc
	v_lshlrev_b32_e32 v22, 2, v17
	v_xor_b32_e32 v17, 16, v4
	v_cmp_lt_i32_e32 vcc, v17, v5
	s_mov_b64 s[2:3], 0x5d85000
	v_lshl_or_b32 v2, v148, 4, v2
	v_cndmask_b32_e32 v17, v4, v17, vcc
	v_lshlrev_b32_e32 v23, 2, v17
	v_xor_b32_e32 v17, 8, v4
	v_cmp_lt_i32_e32 vcc, v17, v5
	s_ashr_i32 s5, s4, 31
	v_lshl_add_u64 v[2:3], s[74:75], 0, v[2:3]
	v_cndmask_b32_e32 v17, v4, v17, vcc
	v_lshlrev_b32_e32 v24, 2, v17
	v_xor_b32_e32 v17, 4, v4
	v_cmp_lt_i32_e32 vcc, v17, v5
	s_lshl_b64 s[8:9], s[4:5], 12
	s_lshl_b64 s[10:11], s[4:5], 13
	v_cndmask_b32_e32 v17, v4, v17, vcc
	v_lshlrev_b32_e32 v25, 2, v17
	v_xor_b32_e32 v17, 2, v4
	v_cmp_lt_i32_e32 vcc, v17, v5
	s_mov_b64 s[12:13], 0
	s_mov_b32 s5, 0x81ff
	v_cndmask_b32_e32 v17, v4, v17, vcc
	v_lshlrev_b32_e32 v26, 2, v17
	v_xor_b32_e32 v17, 1, v4
	v_cmp_lt_i32_e32 vcc, v17, v5
	s_nop 1
	v_cndmask_b32_e32 v4, v4, v17, vcc
	v_ashrrev_i32_e32 v17, 31, v16
	v_lshlrev_b32_e32 v27, 2, v4
	v_lshlrev_b64 v[4:5], 12, v[16:17]
	v_lshl_or_b32 v4, v148, 3, v4
	v_lshl_add_u64 v[4:5], s[76:77], 0, v[4:5]
	v_lshl_add_u64 v[18:19], v[4:5], 0, s[2:3]
	s_mov_b64 s[2:3], 0x10000000
	v_lshl_add_u64 v[20:21], v[2:3], 0, s[2:3]
	s_movk_i32 s2, 0x1000
	v_mov_b32_e32 v17, 0x358637bd
	s_mov_b32 s3, 0x800000
	global_load_dwordx4 v[96:99], v[6:7], off
	global_load_dwordx4 v[100:103], v[6:7], off offset:1024
	global_load_dwordx4 v[104:107], v[6:7], off offset:2048
	global_load_dwordx4 v[108:111], v[6:7], off offset:3072
	global_load_dwordx4 v[112:115], v[8:9], off
	global_load_dwordx4 v[116:119], v[10:11], off
	global_load_dwordx4 v[120:123], v[12:13], off
	global_load_dwordx4 v[124:127], v[14:15], off
; __device__ __forceinline__ unsigned cvtpk(float lo, float hi) { unsigned r; asm volatile("v_cvt_pk_bf16_f32 %0, %1, %2" : "=v"(r) : "v"(lo), "v"(hi)); return r; }
; __device__ __forceinline__ void norm_rows_mixed(const bf16_t* xb, const float* xs, const float* g, bf16_t* xn) {
;     ...
;     for (int row = MP + gw; row < MT; row += nw) {
;         const float* xr = xs + (size_t)(row - MP) * DM; f32x4 v[8]; float ss = 0.f;
; #pragma unroll
;         for (int i = 0; i < 8; ++i) { v[i] = *(const f32x4*)(xr + (i * 64 + lane) * 4); ss += v[i][0] * v[i][0] + v[i][1] * v[i][1] + v[i][2] * v[i][2] + v[i][3] * v[i][3]; }
;         ss = wave_sum(ss); const float rs = rsqrtf(ss * (1.0f / DM) + EPS);
; #pragma unroll
;         for (int i = 0; i < 8; ++i) { const f32x4 gg = *(const f32x4*)(g + (i * 64 + lane) * 4);
;             u32x2 o; o.x = cvtpk(v[i][0] * rs * gg[0], v[i][1] * rs * gg[1]); o.y = cvtpk(v[i][2] * rs * gg[2], v[i][3] * rs * gg[3]);
;             *(u32x2*)(xn + (size_t)row * DM + (i * 64 + lane) * 4) = o; }
;     }
.LBB0_312:
	v_add_co_u32_e32 v2, vcc, s2, v20
	global_load_dwordx4 v[28:31], v[20:21], off
	global_load_dwordx4 v[32:35], v[20:21], off offset:1024
	global_load_dwordx4 v[36:39], v[20:21], off offset:2048
	global_load_dwordx4 v[40:43], v[20:21], off offset:3072
	v_addc_co_u32_e32 v3, vcc, 0, v21, vcc
	global_load_dwordx4 v[44:47], v[2:3], off
	global_load_dwordx4 v[48:51], v[2:3], off offset:1024
	global_load_dwordx4 v[52:55], v[2:3], off offset:2048
	s_nop 0
	global_load_dwordx4 v[2:5], v[2:3], off offset:3072
	s_nop 0
	v_add_u32_e32 v16, s4, v16
	v_lshl_add_u64 v[20:21], v[20:21], 0, s[10:11]
	s_waitcnt vmcnt(0)
	v_mul_f32_e32 v76, v29, v29
	v_mul_f32_e32 v77, v33, v33
	v_mul_f32_e32 v78, v37, v37
	v_fmac_f32_e32 v76, v28, v28
	v_fmac_f32_e32 v77, v32, v32
	v_mul_f32_e32 v79, v41, v41
	v_fmac_f32_e32 v78, v36, v36
	v_mov_b32_e32 v62, v45
	v_mov_b32_e32 v63, v49
	v_mov_b32_e32 v70, v53
	v_mov_b32_e32 v71, v3
	v_fmac_f32_e32 v76, v30, v30
	v_fmac_f32_e32 v77, v34, v34
	v_fmac_f32_e32 v79, v40, v40
	v_mov_b32_e32 v60, v44
	v_mov_b32_e32 v61, v48
	v_mov_b32_e32 v68, v52
	v_mov_b32_e32 v69, v2
	v_fmac_f32_e32 v78, v38, v38
	v_pk_mul_f32 v[62:63], v[62:63], v[62:63]
	v_pk_mul_f32 v[70:71], v[70:71], v[70:71]
	v_fmac_f32_e32 v76, v31, v31
	v_fmac_f32_e32 v77, v35, v35
	v_mov_b32_e32 v64, v46
	v_mov_b32_e32 v65, v50
	v_fmac_f32_e32 v79, v42, v42
	v_fmac_f32_e32 v78, v39, v39
	v_pk_fma_f32 v[60:61], v[60:61], v[60:61], v[62:63]
	v_pk_fma_f32 v[62:63], v[68:69], v[68:69], v[70:71]
	v_add_f32_e32 v68, v76, v77
	v_mov_b32_e32 v66, v47
	v_mov_b32_e32 v67, v51
	v_fmac_f32_e32 v79, v43, v43
	v_pk_fma_f32 v[60:61], v[64:65], v[64:65], v[60:61]
	v_add_f32_e32 v64, v68, v78
	v_mov_b32_e32 v72, v54
	v_mov_b32_e32 v73, v4
	v_pk_fma_f32 v[60:61], v[66:67], v[66:67], v[60:61]
	v_add_f32_e32 v64, v64, v79
	v_mov_b32_e32 v74, v55
	v_mov_b32_e32 v75, v5
	v_pk_fma_f32 v[62:63], v[72:73], v[72:73], v[62:63]
	v_add_f32_e32 v60, v64, v60
	v_pk_fma_f32 v[62:63], v[74:75], v[74:75], v[62:63]
	v_add_f32_e32 v60, v60, v61
	v_add_f32_e32 v60, v60, v62
	v_add_f32_e32 v60, v60, v63
	ds_bpermute_b32 v61, v22, v60
	s_waitcnt lgkmcnt(0)
	v_add_f32_e32 v60, v60, v61
	ds_bpermute_b32 v61, v23, v60
	s_waitcnt lgkmcnt(0)
	v_add_f32_e32 v60, v60, v61
	ds_bpermute_b32 v61, v24, v60
	s_waitcnt lgkmcnt(0)
	v_add_f32_e32 v60, v60, v61
	ds_bpermute_b32 v61, v25, v60
	s_waitcnt lgkmcnt(0)
	v_add_f32_e32 v60, v60, v61
	ds_bpermute_b32 v61, v26, v60
	s_waitcnt lgkmcnt(0)
	v_add_f32_e32 v60, v60, v61
	ds_bpermute_b32 v61, v27, v60
	s_waitcnt lgkmcnt(0)
	v_add_f32_e32 v60, v60, v61
	v_fmamk_f32 v60, v60, 0x3a000000, v17
	v_mul_f32_e32 v61, 0x4b800000, v60
	v_cmp_gt_f32_e32 vcc, s3, v60
	s_nop 1
	v_cndmask_b32_e32 v60, v60, v61, vcc
	v_rsq_f32_e32 v60, v60
	s_nop 0
	v_mul_f32_e32 v61, 0x45800000, v60
	v_cndmask_b32_e32 v60, v60, v61, vcc
	v_mul_f32_e32 v28, v28, v60
	v_mul_f32_e32 v29, v29, v60
	v_mul_f32_e32 v30, v30, v60
	v_mul_f32_e32 v31, v31, v60
	v_mul_f32_e32 v28, v96, v28
	v_mul_f32_e32 v29, v97, v29
	v_mul_f32_e32 v30, v98, v30
	v_mul_f32_e32 v31, v99, v31
	v_cvt_pk_bf16_f32 v28, v28, v29
	v_cvt_pk_bf16_f32 v29, v30, v31
	global_store_dwordx2 v[18:19], v[28:29], off
	v_mul_f32_e32 v32, v32, v60
	v_mul_f32_e32 v33, v33, v60
	v_mul_f32_e32 v34, v34, v60
	v_mul_f32_e32 v35, v35, v60
	v_mul_f32_e32 v2, v2, v60
	v_mul_f32_e32 v3, v3, v60
	v_cmp_lt_i32_e32 vcc, s5, v16
	v_mul_f32_e32 v4, v4, v60
	v_mul_f32_e32 v5, v5, v60
	s_or_b64 s[12:13], vcc, s[12:13]
	v_mul_f32_e32 v28, v100, v32
	v_mul_f32_e32 v29, v101, v33
	v_mul_f32_e32 v30, v102, v34
	v_mul_f32_e32 v31, v103, v35
	v_cvt_pk_bf16_f32 v28, v28, v29
	v_cvt_pk_bf16_f32 v29, v30, v31
	global_store_dwordx2 v[18:19], v[28:29], off offset:512
	v_mul_f32_e32 v32, v36, v60
	v_mul_f32_e32 v33, v37, v60
	v_mul_f32_e32 v34, v38, v60
	v_mul_f32_e32 v35, v39, v60
	v_mul_f32_e32 v28, v104, v32
	v_mul_f32_e32 v29, v105, v33
	v_mul_f32_e32 v30, v106, v34
	v_mul_f32_e32 v31, v107, v35
	v_cvt_pk_bf16_f32 v28, v28, v29
	v_cvt_pk_bf16_f32 v29, v30, v31
	global_store_dwordx2 v[18:19], v[28:29], off offset:1024
	v_mul_f32_e32 v32, v40, v60
	v_mul_f32_e32 v33, v41, v60
	v_mul_f32_e32 v34, v42, v60
	v_mul_f32_e32 v35, v43, v60
	v_mul_f32_e32 v28, v108, v32
	v_mul_f32_e32 v29, v109, v33
	v_mul_f32_e32 v30, v110, v34
	v_mul_f32_e32 v31, v111, v35
	v_cvt_pk_bf16_f32 v28, v28, v29
	v_cvt_pk_bf16_f32 v29, v30, v31
	global_store_dwordx2 v[18:19], v[28:29], off offset:1536
	v_mul_f32_e32 v32, v44, v60
	v_mul_f32_e32 v33, v45, v60
	v_mul_f32_e32 v34, v46, v60
	v_mul_f32_e32 v35, v47, v60
	v_mul_f32_e32 v28, v32, v112
	v_mul_f32_e32 v29, v33, v113
	v_mul_f32_e32 v30, v34, v114
	v_mul_f32_e32 v31, v35, v115
	v_cvt_pk_bf16_f32 v28, v28, v29
	v_cvt_pk_bf16_f32 v29, v30, v31
	global_store_dwordx2 v[18:19], v[28:29], off offset:2048
	v_mul_f32_e32 v32, v48, v60
	v_mul_f32_e32 v33, v49, v60
	v_mul_f32_e32 v34, v50, v60
	v_mul_f32_e32 v35, v51, v60
	v_mul_f32_e32 v28, v32, v116
	v_mul_f32_e32 v29, v33, v117
	v_mul_f32_e32 v30, v34, v118
	v_mul_f32_e32 v31, v35, v119
	v_cvt_pk_bf16_f32 v28, v28, v29
	v_cvt_pk_bf16_f32 v29, v30, v31
	global_store_dwordx2 v[18:19], v[28:29], off offset:2560
	v_mul_f32_e32 v32, v52, v60
	v_mul_f32_e32 v33, v53, v60
	v_mul_f32_e32 v34, v54, v60
	v_mul_f32_e32 v35, v55, v60
	v_mul_f32_e32 v28, v32, v120
	v_mul_f32_e32 v29, v33, v121
	v_mul_f32_e32 v30, v34, v122
	v_mul_f32_e32 v31, v35, v123
	v_cvt_pk_bf16_f32 v28, v28, v29
	v_cvt_pk_bf16_f32 v29, v30, v31
	global_store_dwordx2 v[18:19], v[28:29], off offset:3072
	v_mul_f32_e32 v2, v2, v124
	v_mul_f32_e32 v3, v3, v125
	v_mul_f32_e32 v4, v4, v126
	v_mul_f32_e32 v5, v5, v127
	v_cvt_pk_bf16_f32 v2, v2, v3
	v_cvt_pk_bf16_f32 v3, v4, v5
	global_store_dwordx2 v[18:19], v[2:3], off offset:3584
	v_lshl_add_u64 v[18:19], v[18:19], 0, s[8:9]
	s_andn2_b64 exec, exec, s[12:13]
	s_cbranch_execnz .LBB0_312

; __device__ __forceinline__ unsigned cvtpk(float lo, float hi) { unsigned r; asm volatile("v_cvt_pk_bf16_f32 %0, %1, %2" : "=v"(r) : "v"(lo), "v"(hi)); return r; }
; __global__ void __launch_bounds__(512, 2) mega(Args a) {
;     ...
;         for (int row = gw; row < MT; row += nw) {
;             const float* z = zc + (size_t)row * ZCW; const int kr_ = keyrow_of(row);
;             const int pos = (row < MP) ? (row & (SEQ - 1)) : PAST + ((row - MP) & 63);
;             { const f32x4 x0 = *(const f32x4*)(z + lane * 8), x1 = *(const f32x4*)(z + lane * 8 + 4);
;               float ss = x0[0] * x0[0] + x0[1] * x0[1] + x0[2] * x0[2] + x0[3] * x0[3] + x1[0] * x1[0] + x1[1] * x1[1] + x1[2] * x1[2] + x1[3] * x1[3];
;               ss = wave_sum(ss); const float rs = rsqrtf(ss * (1.0f / 512.0f) + EPS);
;               const f32x4 g0 = *(const f32x4*)(a.in[17] + lane * 8), g1 = *(const f32x4*)(a.in[17] + lane * 8 + 4);
;               u32x4 w = {cvtpk(x0[0] * rs * g0[0], x0[1] * rs * g0[1]), cvtpk(x0[2] * rs * g0[2], x0[3] * rs * g0[3]), cvtpk(x1[0] * rs * g1[0], x1[1] * rs * g1[1]), cvtpk(x1[2] * rs * g1[2], x1[3] * rs * g1[3])};
;               *(u32x4*)(cqn + (size_t)row * 512 + lane * 8) = w; }
;             { const f32x4 x = *(const f32x4*)(z + 512 + lane * 4); float ss = x[0] * x[0] + x[1] * x[1] + x[2] * x[2] + x[3] * x[3];
;               ss = wave_sum(ss); const float rs = rsqrtf(ss * (1.0f / 256.0f) + EPS); const f32x4 gg = *(const f32x4*)(a.in[19] + lane * 4);
;               const f32x4 yv = {x[0] * rs * gg[0], x[1] * rs * gg[1], x[2] * rs * gg[2], x[3] * rs * gg[3]};
;               float* o = (row < MP) ? out + O_CKVP + (size_t)row * 256 : out + O_CKVS + (size_t)(row - MP) * 256; *(f32x4*)(o + lane * 4) = yv;
;               u32x2 w; w.x = cvtpk(yv[0], yv[1]); w.y = cvtpk(yv[2], yv[3]); *(u32x2*)(ckva + (size_t)kr_ * 256 + lane * 4) = w; }
;             { const float x = z[768 + lane]; const float xo = __shfl_xor(x, 32); const int fi = lane & 31;
;               const float c = ropetab[((size_t)pos * 32 + fi) * 2], s = ropetab[((size_t)pos * 32 + fi) * 2 + 1];
;               const float yv = (lane < 32) ? (x * c - xo * s) : (xo * s + x * c);
;               float* o = (row < MP) ? out + O_KRP + (size_t)row * 64 : out + O_KRS + (size_t)(row - MP) * 64; o[lane] = yv;
;               kra[(size_t)kr_ * 64 + lane] = (bf16_t)(cvtpk(yv, yv) & 0xffffu); }
;         }
.LBB0_995:
	s_or_b64 exec, exec, s[30:31]
	v_lshl_add_u64 v[40:41], s[76:77], 0, v[20:21]
	v_lshl_add_u64 v[44:45], v[40:41], 0, s[28:29]
	v_add_co_u32_e32 v40, vcc, 0x24505000, v40
	v_readlane_b32 s24, v244, 26
	s_nop 0
	v_addc_co_u32_e32 v41, vcc, 0, v41, vcc
	global_load_dwordx4 v[40:43], v[40:41], off
	s_nop 0
	global_load_dwordx4 v[44:47], v[44:45], off offset:16
	s_nop 0
	global_load_dwordx4 v[48:51], v[6:7], off
	global_load_dwordx4 v[52:55], v[6:7], off offset:16
	v_readlane_b32 s25, v244, 27
	v_lshl_add_u64 v[30:31], s[74:75], 0, v[30:31]
	v_lshl_add_u64 v[20:21], v[20:21], 0, s[20:21]
	v_lshl_add_u64 v[76:77], s[76:77], 0, v[18:19]
	global_load_dwordx4 v[80:83], v[76:77], off
	global_load_dwordx4 v[84:87], v[8:9], off
	v_lshl_add_u64 v[78:79], s[76:77], 0, v[22:23]
	global_load_dword v88, v[78:79], off
	v_or_b32_e32 v72, 0x1000, v25
	v_and_b32_e32 v73, 0x7ff, v2
	v_cndmask_b32_e64 v72, v72, v73, s[6:7]
	v_mov_b32_e32 v73, v5
	v_lshl_or_b32 v72, v72, 6, v32
	v_lshl_add_u64 v[72:73], v[72:73], 2, s[24:25]
	global_load_dwordx2 v[90:91], v[72:73], off
	s_waitcnt vmcnt(4)
	v_mul_f32_e32 v27, v41, v41
	v_fmac_f32_e32 v27, v40, v40
	v_fmac_f32_e32 v27, v42, v42
	v_pk_mul_f32 v[58:59], v[44:45], v[44:45]
	v_fmac_f32_e32 v27, v43, v43
	v_add_f32_e32 v27, v58, v27
	v_pk_mul_f32 v[56:57], v[46:47], v[46:47]
	v_add_f32_e32 v27, v59, v27
	v_add_f32_e32 v27, v56, v27
	v_add_f32_e32 v27, v57, v27
	ds_bpermute_b32 v56, v33, v27
	v_lshl_add_u64 v[58:59], s[76:77], 0, v[18:19]
	v_lshl_add_u64 v[18:19], v[18:19], 0, s[20:21]
	s_waitcnt lgkmcnt(0)
	v_add_f32_e32 v27, v27, v56
	ds_bpermute_b32 v56, v34, v27
	s_waitcnt lgkmcnt(0)
	v_add_f32_e32 v27, v27, v56
	ds_bpermute_b32 v56, v35, v27
	s_waitcnt lgkmcnt(0)
	v_add_f32_e32 v27, v27, v56
	ds_bpermute_b32 v56, v36, v27
	s_waitcnt lgkmcnt(0)
	v_add_f32_e32 v27, v27, v56
	ds_bpermute_b32 v56, v37, v27
	s_waitcnt lgkmcnt(0)
	v_add_f32_e32 v27, v27, v56
	ds_bpermute_b32 v56, v38, v27
	s_waitcnt lgkmcnt(0)
	v_add_f32_e32 v27, v27, v56
	v_fmamk_f32 v27, v27, 0x3b000000, v39
	v_mul_f32_e32 v56, 0x4b800000, v27
	v_cmp_gt_f32_e32 vcc, s3, v27
	s_nop 1
	v_cndmask_b32_e32 v27, v27, v56, vcc
	v_rsq_f32_e32 v27, v27
	v_lshl_add_u64 v[56:57], s[76:77], 0, v[14:15]
	v_lshl_add_u64 v[14:15], v[14:15], 0, s[18:19]
	v_mul_f32_e32 v60, 0x45800000, v27
	v_cndmask_b32_e32 v27, v27, v60, vcc
	v_mul_f32_e32 v40, v40, v27
	v_mul_f32_e32 v41, v41, v27
	v_mul_f32_e32 v42, v42, v27
	v_mul_f32_e32 v43, v43, v27
	v_mul_f32_e32 v44, v44, v27
	v_mul_f32_e32 v45, v45, v27
	v_mul_f32_e32 v46, v46, v27
	v_mul_f32_e32 v27, v47, v27
	v_mul_f32_e32 v40, v48, v40
	v_mul_f32_e32 v41, v49, v41
	v_mul_f32_e32 v42, v50, v42
	v_mul_f32_e32 v43, v51, v43
	v_mul_f32_e32 v44, v52, v44
	v_mul_f32_e32 v45, v53, v45
	v_mul_f32_e32 v46, v54, v46
	v_mul_f32_e32 v27, v55, v27
	v_cvt_pk_bf16_f32 v40, v40, v41
	v_cvt_pk_bf16_f32 v41, v42, v43
	v_cvt_pk_bf16_f32 v42, v44, v45
	v_cvt_pk_bf16_f32 v43, v46, v27
	global_store_dwordx4 v[56:57], v[40:43], off
	v_or_b32_e32 v56, 0x1000, v25
	v_mov_b32_e32 v25, v5
	v_and_b32_e32 v55, 0x7ff, v2
	v_lshl_add_u64 v[52:53], s[76:77], 0, v[22:23]
	v_lshl_add_u64 v[22:23], v[22:23], 0, s[20:21]
	s_waitcnt vmcnt(4)
	v_pk_mul_f32 v[50:51], v[80:81], v[80:81]
	v_pk_mul_f32 v[48:49], v[82:83], v[82:83]
	v_add_f32_e32 v27, v50, v51
	v_add_f32_e32 v27, v48, v27
	v_add_f32_e32 v27, v49, v27
	ds_bpermute_b32 v48, v33, v27
	s_waitcnt lgkmcnt(0)
	v_add_f32_e32 v27, v27, v48
	ds_bpermute_b32 v48, v34, v27
	s_waitcnt lgkmcnt(0)
	v_add_f32_e32 v27, v27, v48
	ds_bpermute_b32 v48, v35, v27
	s_waitcnt lgkmcnt(0)
	v_add_f32_e32 v27, v27, v48
	ds_bpermute_b32 v48, v36, v27
	s_waitcnt lgkmcnt(0)
	v_add_f32_e32 v27, v27, v48
	ds_bpermute_b32 v50, v37, v27
	v_lshlrev_b64 v[48:49], 10, v[4:5]
	v_lshl_add_u64 v[48:49], s[16:17], 0, v[48:49]
	v_cndmask_b32_e64 v49, v49, v17, s[6:7]
	v_cndmask_b32_e64 v48, v48, v16, s[6:7]
	s_waitcnt lgkmcnt(0)
	v_add_f32_e32 v27, v27, v50
	ds_bpermute_b32 v54, v38, v27
	v_lshl_add_u64 v[48:49], v[48:49], 0, v[24:25]
	v_lshlrev_b64 v[50:51], 9, v[28:29]
	v_lshl_add_u64 v[50:51], v[10:11], 0, v[50:51]
	v_lshlrev_b64 v[28:29], 7, v[28:29]
	s_waitcnt lgkmcnt(0)
	v_add_f32_e32 v27, v27, v54
	v_fmamk_f32 v27, v27, 0x3b800000, v39
	v_mul_f32_e32 v54, 0x4b800000, v27
	v_cmp_gt_f32_e32 vcc, s3, v27
	v_lshl_add_u64 v[28:29], v[12:13], 0, v[28:29]
	v_lshl_add_u64 v[16:17], v[16:17], 0, s[18:19]
	v_cndmask_b32_e32 v27, v27, v54, vcc
	v_rsq_f32_e32 v27, v27
	s_nop 0
	v_mul_f32_e32 v25, 0x45800000, v27
	v_cndmask_b32_e32 v54, v27, v25, vcc
	v_pk_mul_f32 v[40:41], v[80:81], v[54:55] op_sel_hi:[1,0]
	v_pk_mul_f32 v[42:43], v[82:83], v[54:55] op_sel_hi:[1,0]
	s_waitcnt vmcnt(3)
	v_pk_mul_f32 v[40:41], v[84:85], v[40:41]
	v_pk_mul_f32 v[42:43], v[86:87], v[42:43]
	global_store_dwordx4 v[48:49], v[40:43], off
	v_cndmask_b32_e64 v27, v56, v55, s[6:7]
	s_nop 0
	v_cvt_pk_bf16_f32 v40, v40, v41
	v_cvt_pk_bf16_f32 v41, v42, v43
	global_store_dwordx2 v[50:51], v[40:41], off
	v_mov_b32_e32 v41, v5
	v_lshl_or_b32 v40, v27, 6, v32
	v_lshl_add_u64 v[40:41], v[40:41], 2, s[24:25]
	v_cndmask_b32_e64 v42, v4, v2, s[6:7]
	v_cndmask_b32_e64 v43, 0, v3, s[6:7]
	v_lshl_add_u64 v[2:3], v[2:3], 0, s[12:13]
	v_lshlrev_b64 v[42:43], 8, v[42:43]
	v_mov_b32_e32 v27, v5
	v_cmp_lt_i32_e32 vcc, s14, v2
	v_lshl_add_u64 v[30:31], v[30:31], 0, v[42:43]
	s_or_b64 s[22:23], vcc, s[22:23]
	v_lshl_add_u64 v[30:31], v[30:31], 0, v[26:27]
	s_waitcnt vmcnt(3)
	ds_bpermute_b32 v4, v33, v88
	s_waitcnt vmcnt(3) lgkmcnt(0)
	v_mul_f32_e32 v4, v91, v4
	v_cndmask_b32_e64 v4, v4, -v4, s[4:5]
	v_fmac_f32_e32 v4, v88, v90
	global_store_dword v[30:31], v4, off
	v_cvt_pk_bf16_f32 v4, v4, v4
	global_store_short v[28:29], v4, off
	s_andn2_b64 exec, exec, s[22:23]
	s_cbranch_execz .LBB0_1000

; __device__ __forceinline__ unsigned cvtpk(float lo, float hi) { unsigned r; asm volatile("v_cvt_pk_bf16_f32 %0, %1, %2" : "=v"(r) : "v"(lo), "v"(hi)); return r; }
; __device__ __forceinline__ void norm_rows_mixed(const bf16_t* xb, const float* xs, const float* g, bf16_t* xn) {
;     ...
;     for (int row = MP + gw; row < MT; row += nw) {
;         const float* xr = xs + (size_t)(row - MP) * DM; f32x4 v[8]; float ss = 0.f;
; #pragma unroll
;         for (int i = 0; i < 8; ++i) { v[i] = *(const f32x4*)(xr + (i * 64 + lane) * 4); ss += v[i][0] * v[i][0] + v[i][1] * v[i][1] + v[i][2] * v[i][2] + v[i][3] * v[i][3]; }
;         ss = wave_sum(ss); const float rs = rsqrtf(ss * (1.0f / DM) + EPS);
; #pragma unroll
;         for (int i = 0; i < 8; ++i) { const f32x4 gg = *(const f32x4*)(g + (i * 64 + lane) * 4);
;             u32x2 o; o.x = cvtpk(v[i][0] * rs * gg[0], v[i][1] * rs * gg[1]); o.y = cvtpk(v[i][2] * rs * gg[2], v[i][3] * rs * gg[3]);
;             *(u32x2*)(xn + (size_t)row * DM + (i * 64 + lane) * 4) = o; }
;     }
.LBB0_1425:
	s_or_b64 exec, exec, s[6:7]
	s_movk_i32 s1, 0x200
	v_cmp_gt_i32_e32 vcc, s1, v2
	s_and_saveexec_b64 s[6:7], vcc
	s_cbranch_execz .LBB0_1428
	v_mbcnt_hi_u32_b32 v4, -1, v147
	v_and_b32_e32 v5, 64, v4
	v_add_u32_e32 v5, 64, v5
	v_xor_b32_e32 v17, 32, v4
	v_cmp_lt_i32_e32 vcc, v17, v5
	v_add_u32_e32 v16, 0x8000, v2
	v_lshlrev_b64 v[2:3], 13, v[2:3]
	v_cndmask_b32_e32 v17, v4, v17, vcc
	v_lshlrev_b32_e32 v22, 2, v17
	v_xor_b32_e32 v17, 16, v4
	v_cmp_lt_i32_e32 vcc, v17, v5
	s_mov_b64 s[2:3], 0x5d85000
	v_lshl_or_b32 v2, v148, 4, v2
	v_cndmask_b32_e32 v17, v4, v17, vcc
	v_lshlrev_b32_e32 v23, 2, v17
	v_xor_b32_e32 v17, 8, v4
	v_cmp_lt_i32_e32 vcc, v17, v5
	s_ashr_i32 s1, s0, 31
	v_lshl_add_u64 v[2:3], s[74:75], 0, v[2:3]
	v_cndmask_b32_e32 v17, v4, v17, vcc
	v_lshlrev_b32_e32 v24, 2, v17
	v_xor_b32_e32 v17, 4, v4
	v_cmp_lt_i32_e32 vcc, v17, v5
	s_lshl_b64 s[8:9], s[0:1], 12
	s_lshl_b64 s[10:11], s[0:1], 13
	v_cndmask_b32_e32 v17, v4, v17, vcc
	v_lshlrev_b32_e32 v25, 2, v17
	v_xor_b32_e32 v17, 2, v4
	v_cmp_lt_i32_e32 vcc, v17, v5
	s_mov_b64 s[12:13], 0
	s_movk_i32 s1, 0x1000
	v_cndmask_b32_e32 v17, v4, v17, vcc
	v_lshlrev_b32_e32 v26, 2, v17
	v_xor_b32_e32 v17, 1, v4
	v_cmp_lt_i32_e32 vcc, v17, v5
	s_nop 1
	v_cndmask_b32_e32 v4, v4, v17, vcc
	v_ashrrev_i32_e32 v17, 31, v16
	v_lshlrev_b32_e32 v27, 2, v4
	v_lshlrev_b64 v[4:5], 12, v[16:17]
	v_lshl_or_b32 v4, v148, 3, v4
	v_lshl_add_u64 v[4:5], s[76:77], 0, v[4:5]
	v_lshl_add_u64 v[18:19], v[4:5], 0, s[2:3]
	s_mov_b64 s[2:3], 0x10000000
	v_lshl_add_u64 v[20:21], v[2:3], 0, s[2:3]
	v_mov_b32_e32 v17, 0x358637bd
	s_mov_b32 s2, 0x800000
	s_mov_b32 s3, 0x81ff
	global_load_dwordx4 v[96:99], v[6:7], off
	global_load_dwordx4 v[100:103], v[6:7], off offset:1024
	global_load_dwordx4 v[104:107], v[6:7], off offset:2048
	global_load_dwordx4 v[108:111], v[6:7], off offset:3072
	global_load_dwordx4 v[112:115], v[8:9], off
	global_load_dwordx4 v[116:119], v[10:11], off
	global_load_dwordx4 v[120:123], v[12:13], off
	global_load_dwordx4 v[124:127], v[14:15], off
; __device__ __forceinline__ unsigned cvtpk(float lo, float hi) { unsigned r; asm volatile("v_cvt_pk_bf16_f32 %0, %1, %2" : "=v"(r) : "v"(lo), "v"(hi)); return r; }
; __device__ __forceinline__ void norm_rows_mixed(const bf16_t* xb, const float* xs, const float* g, bf16_t* xn) {
;     ...
;     for (int row = MP + gw; row < MT; row += nw) {
;         const float* xr = xs + (size_t)(row - MP) * DM; f32x4 v[8]; float ss = 0.f;
; #pragma unroll
;         for (int i = 0; i < 8; ++i) { v[i] = *(const f32x4*)(xr + (i * 64 + lane) * 4); ss += v[i][0] * v[i][0] + v[i][1] * v[i][1] + v[i][2] * v[i][2] + v[i][3] * v[i][3]; }
;         ss = wave_sum(ss); const float rs = rsqrtf(ss * (1.0f / DM) + EPS);
; #pragma unroll
;         for (int i = 0; i < 8; ++i) { const f32x4 gg = *(const f32x4*)(g + (i * 64 + lane) * 4);
;             u32x2 o; o.x = cvtpk(v[i][0] * rs * gg[0], v[i][1] * rs * gg[1]); o.y = cvtpk(v[i][2] * rs * gg[2], v[i][3] * rs * gg[3]);
;             *(u32x2*)(xn + (size_t)row * DM + (i * 64 + lane) * 4) = o; }
;     }
.LBB0_1427:
	v_add_co_u32_e32 v60, vcc, s1, v20
	global_load_dwordx4 v[28:31], v[20:21], off
	global_load_dwordx4 v[32:35], v[20:21], off offset:1024
	global_load_dwordx4 v[36:39], v[20:21], off offset:2048
	global_load_dwordx4 v[40:43], v[20:21], off offset:3072
	v_addc_co_u32_e32 v61, vcc, 0, v21, vcc
	global_load_dwordx4 v[44:47], v[60:61], off
	global_load_dwordx4 v[48:51], v[60:61], off offset:1024
	global_load_dwordx4 v[52:55], v[60:61], off offset:2048
	global_load_dwordx4 v[2:5], v[60:61], off offset:3072
	v_add_u32_e32 v16, s0, v16
	v_lshl_add_u64 v[20:21], v[20:21], 0, s[10:11]
	s_waitcnt vmcnt(0)
	v_mul_f32_e32 v76, v29, v29
	v_mul_f32_e32 v77, v33, v33
	v_mul_f32_e32 v78, v37, v37
	v_fmac_f32_e32 v76, v28, v28
	v_fmac_f32_e32 v77, v32, v32
	v_mul_f32_e32 v79, v41, v41
	v_fmac_f32_e32 v78, v36, v36
	v_mov_b32_e32 v62, v45
	v_mov_b32_e32 v63, v49
	v_mov_b32_e32 v70, v53
	v_mov_b32_e32 v71, v3
	v_fmac_f32_e32 v76, v30, v30
	v_fmac_f32_e32 v77, v34, v34
	v_fmac_f32_e32 v79, v40, v40
	v_mov_b32_e32 v60, v44
	v_mov_b32_e32 v61, v48
	v_mov_b32_e32 v68, v52
	v_mov_b32_e32 v69, v2
	v_fmac_f32_e32 v78, v38, v38
	v_pk_mul_f32 v[62:63], v[62:63], v[62:63]
	v_pk_mul_f32 v[70:71], v[70:71], v[70:71]
	v_fmac_f32_e32 v76, v31, v31
	v_fmac_f32_e32 v77, v35, v35
	v_mov_b32_e32 v64, v46
	v_mov_b32_e32 v65, v50
	v_fmac_f32_e32 v79, v42, v42
	v_fmac_f32_e32 v78, v39, v39
	v_pk_fma_f32 v[60:61], v[60:61], v[60:61], v[62:63]
	v_pk_fma_f32 v[62:63], v[68:69], v[68:69], v[70:71]
	v_add_f32_e32 v68, v76, v77
	v_mov_b32_e32 v66, v47
	v_mov_b32_e32 v67, v51
	v_fmac_f32_e32 v79, v43, v43
	v_pk_fma_f32 v[60:61], v[64:65], v[64:65], v[60:61]
	v_add_f32_e32 v64, v68, v78
	v_mov_b32_e32 v72, v54
	v_mov_b32_e32 v73, v4
	v_pk_fma_f32 v[60:61], v[66:67], v[66:67], v[60:61]
	v_add_f32_e32 v64, v64, v79
	v_mov_b32_e32 v74, v55
	v_mov_b32_e32 v75, v5
	v_pk_fma_f32 v[62:63], v[72:73], v[72:73], v[62:63]
	v_add_f32_e32 v60, v64, v60
	v_pk_fma_f32 v[62:63], v[74:75], v[74:75], v[62:63]
	v_add_f32_e32 v60, v60, v61
	v_add_f32_e32 v60, v60, v62
	v_add_f32_e32 v60, v60, v63
	ds_bpermute_b32 v61, v22, v60
	s_waitcnt lgkmcnt(0)
	v_add_f32_e32 v60, v60, v61
	ds_bpermute_b32 v61, v23, v60
	s_waitcnt lgkmcnt(0)
	v_add_f32_e32 v60, v60, v61
	ds_bpermute_b32 v61, v24, v60
	s_waitcnt lgkmcnt(0)
	v_add_f32_e32 v60, v60, v61
	ds_bpermute_b32 v61, v25, v60
	s_waitcnt lgkmcnt(0)
	v_add_f32_e32 v60, v60, v61
	ds_bpermute_b32 v61, v26, v60
	s_waitcnt lgkmcnt(0)
	v_add_f32_e32 v60, v60, v61
	ds_bpermute_b32 v61, v27, v60
	s_waitcnt lgkmcnt(0)
	v_add_f32_e32 v60, v60, v61
	v_fmamk_f32 v60, v60, 0x3a000000, v17
	v_mul_f32_e32 v61, 0x4b800000, v60
	v_cmp_gt_f32_e32 vcc, s2, v60
	s_nop 1
	v_cndmask_b32_e32 v60, v60, v61, vcc
	v_rsq_f32_e32 v60, v60
	s_nop 0
	v_mul_f32_e32 v61, 0x45800000, v60
	v_cndmask_b32_e32 v60, v60, v61, vcc
	v_mul_f32_e32 v28, v28, v60
	v_mul_f32_e32 v29, v29, v60
	v_mul_f32_e32 v30, v30, v60
	v_mul_f32_e32 v31, v31, v60
	v_mul_f32_e32 v28, v96, v28
	v_mul_f32_e32 v29, v97, v29
	v_mul_f32_e32 v30, v98, v30
	v_mul_f32_e32 v31, v99, v31
	v_cvt_pk_bf16_f32 v28, v28, v29
	v_cvt_pk_bf16_f32 v29, v30, v31
	global_store_dwordx2 v[18:19], v[28:29], off
	v_mul_f32_e32 v32, v32, v60
	v_mul_f32_e32 v33, v33, v60
	v_mul_f32_e32 v34, v34, v60
	v_mul_f32_e32 v35, v35, v60
	v_mul_f32_e32 v2, v2, v60
	v_mul_f32_e32 v3, v3, v60
	v_cmp_lt_i32_e32 vcc, s3, v16
	v_mul_f32_e32 v4, v4, v60
	v_mul_f32_e32 v5, v5, v60
	s_or_b64 s[12:13], vcc, s[12:13]
	v_mul_f32_e32 v28, v100, v32
	v_mul_f32_e32 v29, v101, v33
	v_mul_f32_e32 v30, v102, v34
	v_mul_f32_e32 v31, v103, v35
	v_cvt_pk_bf16_f32 v28, v28, v29
	v_cvt_pk_bf16_f32 v29, v30, v31
	global_store_dwordx2 v[18:19], v[28:29], off offset:512
	v_mul_f32_e32 v32, v36, v60
	v_mul_f32_e32 v33, v37, v60
	v_mul_f32_e32 v34, v38, v60
	v_mul_f32_e32 v35, v39, v60
	v_mul_f32_e32 v28, v104, v32
	v_mul_f32_e32 v29, v105, v33
	v_mul_f32_e32 v30, v106, v34
	v_mul_f32_e32 v31, v107, v35
	v_cvt_pk_bf16_f32 v28, v28, v29
	v_cvt_pk_bf16_f32 v29, v30, v31
	global_store_dwordx2 v[18:19], v[28:29], off offset:1024
	v_mul_f32_e32 v32, v40, v60
	v_mul_f32_e32 v33, v41, v60
	v_mul_f32_e32 v34, v42, v60
	v_mul_f32_e32 v35, v43, v60
	v_mul_f32_e32 v28, v108, v32
	v_mul_f32_e32 v29, v109, v33
	v_mul_f32_e32 v30, v110, v34
	v_mul_f32_e32 v31, v111, v35
	v_cvt_pk_bf16_f32 v28, v28, v29
	v_cvt_pk_bf16_f32 v29, v30, v31
	global_store_dwordx2 v[18:19], v[28:29], off offset:1536
	v_mul_f32_e32 v32, v44, v60
	v_mul_f32_e32 v33, v45, v60
	v_mul_f32_e32 v34, v46, v60
	v_mul_f32_e32 v35, v47, v60
	v_mul_f32_e32 v28, v32, v112
	v_mul_f32_e32 v29, v33, v113
	v_mul_f32_e32 v30, v34, v114
	v_mul_f32_e32 v31, v35, v115
	v_cvt_pk_bf16_f32 v28, v28, v29
	v_cvt_pk_bf16_f32 v29, v30, v31
	global_store_dwordx2 v[18:19], v[28:29], off offset:2048
	v_mul_f32_e32 v32, v48, v60
	v_mul_f32_e32 v33, v49, v60
	v_mul_f32_e32 v34, v50, v60
	v_mul_f32_e32 v35, v51, v60
	v_mul_f32_e32 v28, v32, v116
	v_mul_f32_e32 v29, v33, v117
	v_mul_f32_e32 v30, v34, v118
	v_mul_f32_e32 v31, v35, v119
	v_cvt_pk_bf16_f32 v28, v28, v29
	v_cvt_pk_bf16_f32 v29, v30, v31
	global_store_dwordx2 v[18:19], v[28:29], off offset:2560
	v_mul_f32_e32 v32, v52, v60
	v_mul_f32_e32 v33, v53, v60
	v_mul_f32_e32 v34, v54, v60
	v_mul_f32_e32 v35, v55, v60
	v_mul_f32_e32 v28, v32, v120
	v_mul_f32_e32 v29, v33, v121
	v_mul_f32_e32 v30, v34, v122
	v_mul_f32_e32 v31, v35, v123
	v_cvt_pk_bf16_f32 v28, v28, v29
	v_cvt_pk_bf16_f32 v29, v30, v31
	global_store_dwordx2 v[18:19], v[28:29], off offset:3072
	v_mul_f32_e32 v2, v2, v124
	v_mul_f32_e32 v3, v3, v125
	v_mul_f32_e32 v4, v4, v126
	v_mul_f32_e32 v5, v5, v127
	v_cvt_pk_bf16_f32 v2, v2, v3
	v_cvt_pk_bf16_f32 v3, v4, v5
	global_store_dwordx2 v[18:19], v[2:3], off offset:3584
	v_lshl_add_u64 v[18:19], v[18:19], 0, s[8:9]
	s_andn2_b64 exec, exec, s[12:13]
	s_cbranch_execnz .LBB0_1427

; __global__ void __launch_bounds__(512, 2) mega(Args a) {
;     ...
;         for (int row = MP + gw; row < MT; row += nw) {
;             float* xr = y + (size_t)row * DM; f32x4 v[8]; float ss = 0.f;
; #pragma unroll
;             for (int i = 0; i < 8; ++i) { v[i] = *(const f32x4*)(xr + (i * 64 + lane) * 4); ss += v[i][0] * v[i][0] + v[i][1] * v[i][1] + v[i][2] * v[i][2] + v[i][3] * v[i][3]; }
;             ss = wave_sum(ss); const float rs = rsqrtf(ss * (1.0f / DM) + EPS);
; #pragma unroll
;             for (int i = 0; i < 8; ++i) { const f32x4 gg = *(const f32x4*)(g + (i * 64 + lane) * 4);
;                 *(f32x4*)(xr + (i * 64 + lane) * 4) = (f32x4){v[i][0] * rs * gg[0], v[i][1] * rs * gg[1], v[i][2] * rs * gg[2], v[i][3] * rs * gg[3]}; }
;         }
.LBB0_1694:
	s_or_b64 exec, exec, s[2:3]
	s_movk_i32 s1, 0x200
	v_cmp_gt_i32_e32 vcc, s1, v6
	s_and_saveexec_b64 s[2:3], vcc
	s_cbranch_execz .LBB0_1697
	v_mbcnt_hi_u32_b32 v1, -1, v147
	v_and_b32_e32 v2, 64, v1
	v_add_u32_e32 v2, 64, v2
	s_waitcnt lgkmcnt(0)
	v_xor_b32_e32 v3, 32, v1
	v_cmp_lt_i32_e32 vcc, v3, v2
	v_add_u32_e32 v0, 0x8000, v6
	v_mov_b32_e32 v5, 0
	v_cndmask_b32_e32 v3, v1, v3, vcc
	v_lshlrev_b32_e32 v14, 2, v3
	v_xor_b32_e32 v3, 16, v1
	v_cmp_lt_i32_e32 vcc, v3, v2
	v_or_b32_e32 v6, 0x1000, v4
	v_mov_b32_e32 v7, v5
	v_cndmask_b32_e32 v3, v1, v3, vcc
	v_lshlrev_b32_e32 v15, 2, v3
	v_xor_b32_e32 v3, 8, v1
	v_cmp_lt_i32_e32 vcc, v3, v2
	v_or_b32_e32 v8, 0x1400, v4
	v_mov_b32_e32 v9, v5
	v_cndmask_b32_e32 v3, v1, v3, vcc
	v_lshlrev_b32_e32 v16, 2, v3
	v_xor_b32_e32 v3, 4, v1
	v_cmp_lt_i32_e32 vcc, v3, v2
	v_or_b32_e32 v10, 0x1800, v4
	v_mov_b32_e32 v11, v5
	v_cndmask_b32_e32 v3, v1, v3, vcc
	v_lshlrev_b32_e32 v17, 2, v3
	v_xor_b32_e32 v3, 2, v1
	v_cmp_lt_i32_e32 vcc, v3, v2
	s_mov_b64 s[2:3], 0x1c00
	s_ashr_i32 s1, s0, 31
	v_cndmask_b32_e32 v3, v1, v3, vcc
	v_lshlrev_b32_e32 v18, 2, v3
	v_xor_b32_e32 v3, 1, v1
	v_cmp_lt_i32_e32 vcc, v3, v2
	v_lshl_add_u64 v[6:7], s[72:73], 0, v[6:7]
	v_lshl_add_u64 v[8:9], s[72:73], 0, v[8:9]
	v_cndmask_b32_e32 v1, v1, v3, vcc
	v_lshlrev_b32_e32 v19, 2, v1
	v_ashrrev_i32_e32 v1, 31, v0
	v_lshlrev_b64 v[12:13], 13, v[0:1]
	v_lshl_or_b32 v12, v148, 4, v12
	v_lshl_add_u64 v[2:3], s[72:73], 0, v[4:5]
	v_or_b32_e32 v4, 0x1c00, v4
	v_lshl_add_u64 v[12:13], s[74:75], 0, v[12:13]
	v_lshl_add_u64 v[10:11], s[72:73], 0, v[10:11]
	v_lshl_add_u64 v[4:5], s[72:73], 0, v[4:5]
	v_lshl_add_u64 v[12:13], v[12:13], 0, s[2:3]
	s_lshl_b64 s[2:3], s[0:1], 13
	s_mov_b64 s[4:5], 0
	v_mov_b32_e32 v1, 0x358637bd
	s_mov_b32 s1, 0x800000
	s_mov_b32 s6, 0x81ff
	global_load_dwordx4 v[96:99], v[2:3], off
	global_load_dwordx4 v[100:103], v[2:3], off offset:1024
	global_load_dwordx4 v[104:107], v[2:3], off offset:2048
	global_load_dwordx4 v[108:111], v[2:3], off offset:3072
	global_load_dwordx4 v[112:115], v[6:7], off
	global_load_dwordx4 v[116:119], v[8:9], off
	global_load_dwordx4 v[120:123], v[10:11], off
	global_load_dwordx4 v[124:127], v[4:5], off
; __global__ void __launch_bounds__(512, 2) mega(Args a) {
;     ...
;         for (int row = MP + gw; row < MT; row += nw) {
;             float* xr = y + (size_t)row * DM; f32x4 v[8]; float ss = 0.f;
; #pragma unroll
;             for (int i = 0; i < 8; ++i) { v[i] = *(const f32x4*)(xr + (i * 64 + lane) * 4); ss += v[i][0] * v[i][0] + v[i][1] * v[i][1] + v[i][2] * v[i][2] + v[i][3] * v[i][3]; }
;             ss = wave_sum(ss); const float rs = rsqrtf(ss * (1.0f / DM) + EPS);
; #pragma unroll
;             for (int i = 0; i < 8; ++i) { const f32x4 gg = *(const f32x4*)(g + (i * 64 + lane) * 4);
;                 *(f32x4*)(xr + (i * 64 + lane) * 4) = (f32x4){v[i][0] * rs * gg[0], v[i][1] * rs * gg[1], v[i][2] * rs * gg[2], v[i][3] * rs * gg[3]}; }
;         }
.LBB0_1696:
	v_add_co_u32_e32 v56, vcc, 0xfffff000, v12
	global_load_dwordx4 v[20:23], v[12:13], off offset:-3072
	global_load_dwordx4 v[24:27], v[12:13], off offset:-2048
	global_load_dwordx4 v[28:31], v[12:13], off offset:-1024
	global_load_dwordx4 v[32:35], v[12:13], off
	v_addc_co_u32_e32 v57, vcc, -1, v13, vcc
	global_load_dwordx4 v[36:39], v[56:57], off offset:-3072
	global_load_dwordx4 v[40:43], v[56:57], off offset:-2048
	global_load_dwordx4 v[44:47], v[56:57], off offset:-1024
	global_load_dwordx4 v[48:51], v[12:13], off offset:-4096
	v_add_u32_e32 v0, s0, v0
	s_waitcnt vmcnt(0)
	v_mov_b32_e32 v60, v21
	v_mov_b32_e32 v61, v25
	v_mul_f32_e32 v74, v37, v37
	v_mul_f32_e32 v75, v41, v41
	v_mul_f32_e32 v76, v45, v45
	v_fmac_f32_e32 v74, v36, v36
	v_fmac_f32_e32 v75, v40, v40
	v_mov_b32_e32 v58, v20
	v_mov_b32_e32 v59, v24
	v_pk_mul_f32 v[60:61], v[60:61], v[60:61]
	v_mul_f32_e32 v77, v49, v49
	v_fmac_f32_e32 v76, v44, v44
	v_fmac_f32_e32 v74, v38, v38
	v_fmac_f32_e32 v75, v42, v42
	v_mov_b32_e32 v62, v22
	v_mov_b32_e32 v63, v26
	v_pk_fma_f32 v[58:59], v[58:59], v[58:59], v[60:61]
	v_fmac_f32_e32 v77, v48, v48
	v_fmac_f32_e32 v76, v46, v46
	v_fmac_f32_e32 v74, v39, v39
	v_fmac_f32_e32 v75, v43, v43
	v_mov_b32_e32 v68, v29
	v_mov_b32_e32 v69, v33
	v_pk_fma_f32 v[58:59], v[62:63], v[62:63], v[58:59]
	v_fmac_f32_e32 v77, v50, v50
	v_fmac_f32_e32 v76, v47, v47
	v_add_f32_e32 v62, v74, v75
	v_mov_b32_e32 v64, v23
	v_mov_b32_e32 v65, v27
	v_mov_b32_e32 v66, v28
	v_mov_b32_e32 v67, v32
	v_pk_mul_f32 v[68:69], v[68:69], v[68:69]
	v_fmac_f32_e32 v77, v51, v51
	v_add_f32_e32 v62, v62, v76
	v_mov_b32_e32 v70, v30
	v_mov_b32_e32 v71, v34
	v_pk_fma_f32 v[60:61], v[66:67], v[66:67], v[68:69]
	v_pk_fma_f32 v[58:59], v[64:65], v[64:65], v[58:59]
	v_add_f32_e32 v62, v62, v77
	v_mov_b32_e32 v72, v31
	v_mov_b32_e32 v73, v35
	v_pk_fma_f32 v[60:61], v[70:71], v[70:71], v[60:61]
	v_add_f32_e32 v58, v62, v58
	v_pk_fma_f32 v[60:61], v[72:73], v[72:73], v[60:61]
	v_add_f32_e32 v58, v58, v59
	v_add_f32_e32 v58, v58, v60
	v_add_f32_e32 v58, v58, v61
	ds_bpermute_b32 v59, v14, v58
	s_waitcnt lgkmcnt(0)
	v_add_f32_e32 v58, v58, v59
	ds_bpermute_b32 v59, v15, v58
	s_waitcnt lgkmcnt(0)
	v_add_f32_e32 v58, v58, v59
	ds_bpermute_b32 v59, v16, v58
	s_waitcnt lgkmcnt(0)
	v_add_f32_e32 v58, v58, v59
	ds_bpermute_b32 v59, v17, v58
	s_waitcnt lgkmcnt(0)
	v_add_f32_e32 v58, v58, v59
	ds_bpermute_b32 v59, v18, v58
	s_waitcnt lgkmcnt(0)
	v_add_f32_e32 v58, v58, v59
	ds_bpermute_b32 v59, v19, v58
	s_waitcnt lgkmcnt(0)
	v_add_f32_e32 v58, v58, v59
	v_fmamk_f32 v58, v58, 0x3a000000, v1
	v_mul_f32_e32 v59, 0x4b800000, v58
	v_cmp_gt_f32_e32 vcc, s1, v58
	s_nop 1
	v_cndmask_b32_e32 v58, v58, v59, vcc
	v_rsq_f32_e32 v58, v58
	s_nop 0
	v_mul_f32_e32 v59, 0x45800000, v58
	v_cndmask_b32_e32 v58, v58, v59, vcc
	v_pk_mul_f32 v[36:37], v[58:59], v[36:37] op_sel_hi:[0,1]
	v_pk_mul_f32 v[38:39], v[58:59], v[38:39] op_sel_hi:[0,1]
	v_pk_mul_f32 v[38:39], v[38:39], v[98:99]
	v_pk_mul_f32 v[36:37], v[36:37], v[96:97]
	global_store_dwordx4 v[56:57], v[36:39], off offset:-3072
	s_nop 1
	v_pk_mul_f32 v[42:43], v[58:59], v[42:43] op_sel_hi:[0,1]
	v_pk_mul_f32 v[40:41], v[58:59], v[40:41] op_sel_hi:[0,1]
	v_pk_mul_f32 v[22:23], v[58:59], v[22:23] op_sel_hi:[0,1]
	v_pk_mul_f32 v[20:21], v[58:59], v[20:21] op_sel_hi:[0,1]
	v_pk_mul_f32 v[26:27], v[58:59], v[26:27] op_sel_hi:[0,1]
	v_pk_mul_f32 v[24:25], v[58:59], v[24:25] op_sel_hi:[0,1]
	v_cmp_lt_i32_e32 vcc, s6, v0
	s_or_b64 s[4:5], vcc, s[4:5]
	v_pk_mul_f32 v[36:37], v[40:41], v[100:101]
	v_pk_mul_f32 v[38:39], v[42:43], v[102:103]
	global_store_dwordx4 v[56:57], v[36:39], off offset:-2048
	s_nop 1
	v_pk_mul_f32 v[40:41], v[58:59], v[46:47] op_sel_hi:[0,1]
	v_pk_mul_f32 v[42:43], v[58:59], v[44:45] op_sel_hi:[0,1]
	v_pk_mul_f32 v[36:37], v[42:43], v[104:105]
	v_pk_mul_f32 v[38:39], v[40:41], v[106:107]
	global_store_dwordx4 v[56:57], v[36:39], off offset:-1024
	s_nop 1
	v_pk_mul_f32 v[40:41], v[58:59], v[50:51] op_sel_hi:[0,1]
	v_pk_mul_f32 v[42:43], v[58:59], v[48:49] op_sel_hi:[0,1]
	v_pk_mul_f32 v[36:37], v[42:43], v[108:109]
	v_pk_mul_f32 v[38:39], v[40:41], v[110:111]
	global_store_dwordx4 v[12:13], v[36:39], off offset:-4096
	s_nop 1
	v_pk_mul_f32 v[20:21], v[20:21], v[112:113]
	v_pk_mul_f32 v[22:23], v[22:23], v[114:115]
	global_store_dwordx4 v[12:13], v[20:23], off offset:-3072
	s_nop 1
	v_pk_mul_f32 v[20:21], v[24:25], v[116:117]
	v_pk_mul_f32 v[22:23], v[26:27], v[118:119]
	global_store_dwordx4 v[12:13], v[20:23], off offset:-2048
	s_nop 1
	v_pk_mul_f32 v[24:25], v[58:59], v[30:31] op_sel_hi:[0,1]
	v_pk_mul_f32 v[26:27], v[58:59], v[28:29] op_sel_hi:[0,1]
	v_pk_mul_f32 v[20:21], v[26:27], v[120:121]
	v_pk_mul_f32 v[22:23], v[24:25], v[122:123]
	global_store_dwordx4 v[12:13], v[20:23], off offset:-1024
	s_nop 1
	v_pk_mul_f32 v[24:25], v[58:59], v[34:35] op_sel_hi:[0,1]
	v_pk_mul_f32 v[26:27], v[58:59], v[32:33] op_sel_hi:[0,1]
	v_pk_mul_f32 v[20:21], v[26:27], v[124:125]
	v_pk_mul_f32 v[22:23], v[24:25], v[126:127]
	global_store_dwordx4 v[12:13], v[20:23], off
	s_nop 1
	v_lshl_add_u64 v[12:13], v[12:13], 0, s[2:3]
	s_andn2_b64 exec, exec, s[4:5]
	s_cbranch_execnz .LBB0_1696
